# codepf2: barrier-time code touch clamped per copy so no load leaves .text; rest = v95
# baseline (speedup 1.0000x reference)
; #define RUN_PH(k) if (ph0 <= (k) && (k) < ph1) { if ((k) != ph0) xcd_barrier(xb); run_phase<(k)>(kp, shm); }
; __device__ __forceinline__ void xcd_barrier(const XcdBarrier& b) {
;     asm volatile("s_waitcnt vmcnt(0)" ::: "memory");
;     __syncthreads();
;     if (threadIdx.x == 0) {
;         unsigned* bar = b.bar;
;         __builtin_amdgcn_s_waitcnt(0);
;         unsigned nloc = b.st[0], nx = b.st[1];
;         if (nloc == 0u) { xcd_barrier_complete(bar, b.x, nloc, nx); b.st[0] = nloc; b.st[1] = nx; }
; __global__ void __launch_bounds__(512, 2) mega(Params P, int ph0, int ph1) {
;     ...
;     RUN_PH(0) RUN_PH(1) RUN_PH(2) RUN_PH(3) RUN_PH(4) RUN_PH(5) RUN_PH(6) RUN_PH(7) RUN_PH(8) RUN_PH(9)
;     RUN_PH(10) RUN_PH(11) RUN_PH(12) RUN_PH(13) RUN_PH(14) RUN_PH(15) RUN_PH(16) RUN_PH(17)
.LBB0_5:
	s_or_b64 exec, exec, s[4:5]
	s_load_dwordx2 s[94:95], s[86:87], 0xd8
	s_waitcnt lgkmcnt(0)
	s_cmp_gt_i32 s94, 0
	s_cselect_b64 s[0:1], -1, 0
	s_cmp_lt_i32 s95, 1
	s_cselect_b64 s[2:3], -1, 0
	s_or_b64 s[0:1], s[0:1], s[2:3]
	s_and_b64 vcc, exec, s[0:1]
	s_cbranch_vccnz .LBB0_258
	s_cmp_eq_u32 s94, 0
	s_cbranch_scc1 .LBB0_60
	s_waitcnt vmcnt(0)
	v_cmp_lt_u32_e32 vcc, 63, v0
	s_and_saveexec_b64 s[0:1], vcc
	s_getpc_b64 s[2:3]
	v_lshlrev_b32_e32 v1, 6, v0
	v_min_u32_e32 v1, 0x7fc0, v1
	global_load_dword v1, v1, s[2:3] offset:-4096
	s_mov_b64 exec, s[0:1]
	s_barrier
	s_and_saveexec_b64 s[4:5], s[92:93]
	s_cbranch_execz .LBB0_59
	v_mov_b32_e32 v1, 0
	s_waitcnt vmcnt(0) expcnt(0) lgkmcnt(0)
	ds_read_b32 v3, v1
	ds_read_b32 v2, v1 offset:4
	s_waitcnt lgkmcnt(1)
	v_cmp_ne_u32_e32 vcc, 0, v3
	s_cbranch_vccnz .LBB0_23
	s_add_u32 s6, s88, 0x2e9d8200
	s_addc_u32 s7, s89, 0
	s_add_u32 s8, s88, 0x2e9d8400
	s_addc_u32 s9, s89, 0
	s_add_u32 s12, s88, 0x2e9d8500
	s_addc_u32 s13, s89, 0
	s_add_u32 s14, s88, 0x2e9d8600
	s_addc_u32 s15, s89, 0
	s_add_u32 s16, s88, 0x2e9d8700
	s_addc_u32 s17, s89, 0
	s_add_u32 s18, s88, 0x2e9d8800
	s_addc_u32 s19, s89, 0
	s_add_u32 s20, s88, 0x2e9d8900
	s_addc_u32 s21, s89, 0
	s_add_u32 s22, s88, 0x2e9d8a00
	s_addc_u32 s23, s89, 0
	s_add_u32 s24, s88, 0x2e9d8b00
	s_addc_u32 s25, s89, 0
	s_add_u32 s26, s88, 0x2e9d8c00
	s_addc_u32 s27, s89, 0
	s_add_u32 s28, s88, 0x2e9d8d00
	s_addc_u32 s29, s89, 0
	s_add_u32 s34, s88, 0x2e9d8e00
	s_addc_u32 s35, s89, 0
	s_add_u32 s36, s88, 0x2e9d8f00
	s_addc_u32 s37, s89, 0
	s_add_u32 s38, s88, 0x2e9d9000
	s_addc_u32 s39, s89, 0
	s_load_dwordx2 s[0:1], s[86:87], 0xe0
	s_load_dword s2, s[86:87], 0xe8
	s_add_u32 s40, s88, 0x2e9d9100
	s_addc_u32 s41, s89, 0
	s_add_u32 s42, s88, 0x2e9d9200
	s_addc_u32 s43, s89, 0
	s_waitcnt lgkmcnt(0)
	s_mul_i32 s0, s1, s0
	s_add_u32 s44, s88, 0x2e9d9300
	s_mul_i32 s0, s0, s2
	s_addc_u32 s45, s89, 0
	s_mov_b32 s1, 1
	s_branch .LBB0_11

; #define RUN_PH(k) if (ph0 <= (k) && (k) < ph1) { if ((k) != ph0) xcd_barrier(xb); run_phase<(k)>(kp, shm); }
; __device__ __forceinline__ void xcd_barrier(const XcdBarrier& b) {
;     asm volatile("s_waitcnt vmcnt(0)" ::: "memory");
;     __syncthreads();
;     if (threadIdx.x == 0) {
;         unsigned* bar = b.bar;
;         __builtin_amdgcn_s_waitcnt(0);
;         unsigned nloc = b.st[0], nx = b.st[1];
;         if (nloc == 0u) { xcd_barrier_complete(bar, b.x, nloc, nx); b.st[0] = nloc; b.st[1] = nx; }
; __global__ void __launch_bounds__(512, 2) mega(Params P, int ph0, int ph1) {
;     ...
;     RUN_PH(0) RUN_PH(1) RUN_PH(2) RUN_PH(3) RUN_PH(4) RUN_PH(5) RUN_PH(6) RUN_PH(7) RUN_PH(8) RUN_PH(9)
;     RUN_PH(10) RUN_PH(11) RUN_PH(12) RUN_PH(13) RUN_PH(14) RUN_PH(15) RUN_PH(16) RUN_PH(17)
.LBB0_258:
	s_cmp_gt_i32 s94, 1
	s_cselect_b64 s[0:1], -1, 0
	s_cmp_lt_i32 s95, 2
	s_cselect_b64 s[2:3], -1, 0
	s_or_b64 s[0:1], s[0:1], s[2:3]
	s_and_b64 vcc, exec, s[0:1]
	s_cbranch_vccnz .LBB0_319
	s_cmp_eq_u32 s94, 1
	s_cbranch_scc1 .LBB0_313
	s_waitcnt vmcnt(0)
	v_cmp_lt_u32_e32 vcc, 63, v0
	s_and_saveexec_b64 s[0:1], vcc
	s_getpc_b64 s[2:3]
	v_lshlrev_b32_e32 v1, 6, v0
	v_min_u32_e32 v1, 0x7fc0, v1
	global_load_dword v1, v1, s[2:3] offset:-4096
	s_mov_b64 exec, s[0:1]
	s_barrier
	s_and_saveexec_b64 s[4:5], s[92:93]
	s_cbranch_execz .LBB0_312
	v_mov_b32_e32 v1, 0
	s_waitcnt vmcnt(0) expcnt(0) lgkmcnt(0)
	ds_read_b32 v3, v1
	ds_read_b32 v2, v1 offset:4
	s_waitcnt lgkmcnt(1)
	v_cmp_ne_u32_e32 vcc, 0, v3
	s_cbranch_vccnz .LBB0_276
	s_add_u32 s6, s88, 0x2e9d8200
	s_addc_u32 s7, s89, 0
	s_add_u32 s8, s88, 0x2e9d8400
	s_addc_u32 s9, s89, 0
	s_add_u32 s12, s88, 0x2e9d8500
	s_addc_u32 s13, s89, 0
	s_add_u32 s14, s88, 0x2e9d8600
	s_addc_u32 s15, s89, 0
	s_add_u32 s16, s88, 0x2e9d8700
	s_addc_u32 s17, s89, 0
	s_add_u32 s18, s88, 0x2e9d8800
	s_addc_u32 s19, s89, 0
	s_add_u32 s20, s88, 0x2e9d8900
	s_addc_u32 s21, s89, 0
	s_add_u32 s22, s88, 0x2e9d8a00
	s_addc_u32 s23, s89, 0
	s_add_u32 s24, s88, 0x2e9d8b00
	s_addc_u32 s25, s89, 0
	s_add_u32 s26, s88, 0x2e9d8c00
	s_addc_u32 s27, s89, 0
	s_add_u32 s28, s88, 0x2e9d8d00
	s_addc_u32 s29, s89, 0
	s_add_u32 s34, s88, 0x2e9d8e00
	s_addc_u32 s35, s89, 0
	s_add_u32 s36, s88, 0x2e9d8f00
	s_addc_u32 s37, s89, 0
	s_add_u32 s38, s88, 0x2e9d9000
	s_addc_u32 s39, s89, 0
	s_load_dwordx2 s[0:1], s[86:87], 0xe0
	s_load_dword s2, s[86:87], 0xe8
	s_add_u32 s40, s88, 0x2e9d9100
	s_addc_u32 s41, s89, 0
	s_add_u32 s42, s88, 0x2e9d9200
	s_addc_u32 s43, s89, 0
	s_waitcnt lgkmcnt(0)
	s_mul_i32 s0, s1, s0
	s_add_u32 s44, s88, 0x2e9d9300
	s_mul_i32 s0, s0, s2
	s_addc_u32 s45, s89, 0
	s_mov_b32 s1, 1
	s_branch .LBB0_264

; #define RUN_PH(k) if (ph0 <= (k) && (k) < ph1) { if ((k) != ph0) xcd_barrier(xb); run_phase<(k)>(kp, shm); }
; __device__ __forceinline__ void xcd_barrier(const XcdBarrier& b) {
;     asm volatile("s_waitcnt vmcnt(0)" ::: "memory");
;     __syncthreads();
;     if (threadIdx.x == 0) {
;         unsigned* bar = b.bar;
;         __builtin_amdgcn_s_waitcnt(0);
;         unsigned nloc = b.st[0], nx = b.st[1];
;         if (nloc == 0u) { xcd_barrier_complete(bar, b.x, nloc, nx); b.st[0] = nloc; b.st[1] = nx; }
; __global__ void __launch_bounds__(512, 2) mega(Params P, int ph0, int ph1) {
;     ...
;     RUN_PH(0) RUN_PH(1) RUN_PH(2) RUN_PH(3) RUN_PH(4) RUN_PH(5) RUN_PH(6) RUN_PH(7) RUN_PH(8) RUN_PH(9)
;     RUN_PH(10) RUN_PH(11) RUN_PH(12) RUN_PH(13) RUN_PH(14) RUN_PH(15) RUN_PH(16) RUN_PH(17)
.LBB0_319:
	s_cmp_gt_i32 s94, 2
	s_cselect_b64 s[0:1], -1, 0
	s_cmp_lt_i32 s95, 3
	s_cselect_b64 s[2:3], -1, 0
	s_or_b64 s[0:1], s[0:1], s[2:3]
	s_and_b64 vcc, exec, s[0:1]
	s_cbranch_vccnz .LBB0_436
	s_cmp_eq_u32 s94, 2
	s_cbranch_scc1 .LBB0_374
	s_waitcnt vmcnt(0)
	v_cmp_lt_u32_e32 vcc, 63, v0
	s_and_saveexec_b64 s[0:1], vcc
	s_getpc_b64 s[2:3]
	v_lshlrev_b32_e32 v1, 6, v0
	v_min_u32_e32 v1, 0x7fc0, v1
	global_load_dword v1, v1, s[2:3] offset:-4096
	s_mov_b64 exec, s[0:1]
	s_barrier
	s_and_saveexec_b64 s[4:5], s[92:93]
	s_cbranch_execz .LBB0_373
	v_mov_b32_e32 v1, 0
	s_waitcnt vmcnt(0) expcnt(0) lgkmcnt(0)
	ds_read_b32 v3, v1
	ds_read_b32 v2, v1 offset:4
	s_waitcnt lgkmcnt(1)
	v_cmp_ne_u32_e32 vcc, 0, v3
	s_cbranch_vccnz .LBB0_337
	s_add_u32 s6, s88, 0x2e9d8200
	s_addc_u32 s7, s89, 0
	s_add_u32 s8, s88, 0x2e9d8400
	s_addc_u32 s9, s89, 0
	s_add_u32 s12, s88, 0x2e9d8500
	s_addc_u32 s13, s89, 0
	s_add_u32 s14, s88, 0x2e9d8600
	s_addc_u32 s15, s89, 0
	s_add_u32 s16, s88, 0x2e9d8700
	s_addc_u32 s17, s89, 0
	s_add_u32 s18, s88, 0x2e9d8800
	s_addc_u32 s19, s89, 0
	s_add_u32 s20, s88, 0x2e9d8900
	s_addc_u32 s21, s89, 0
	s_add_u32 s22, s88, 0x2e9d8a00
	s_addc_u32 s23, s89, 0
	s_add_u32 s24, s88, 0x2e9d8b00
	s_addc_u32 s25, s89, 0
	s_add_u32 s26, s88, 0x2e9d8c00
	s_addc_u32 s27, s89, 0
	s_add_u32 s28, s88, 0x2e9d8d00
	s_addc_u32 s29, s89, 0
	s_add_u32 s34, s88, 0x2e9d8e00
	s_addc_u32 s35, s89, 0
	s_add_u32 s36, s88, 0x2e9d8f00
	s_addc_u32 s37, s89, 0
	s_add_u32 s38, s88, 0x2e9d9000
	s_addc_u32 s39, s89, 0
	s_load_dwordx2 s[0:1], s[86:87], 0xe0
	s_load_dword s2, s[86:87], 0xe8
	s_add_u32 s40, s88, 0x2e9d9100
	s_addc_u32 s41, s89, 0
	s_add_u32 s42, s88, 0x2e9d9200
	s_addc_u32 s43, s89, 0
	s_waitcnt lgkmcnt(0)
	s_mul_i32 s0, s1, s0
	s_add_u32 s44, s88, 0x2e9d9300
	s_mul_i32 s0, s0, s2
	s_addc_u32 s45, s89, 0
	s_mov_b32 s1, 1
	s_branch .LBB0_325

; #define RUN_PH(k) if (ph0 <= (k) && (k) < ph1) { if ((k) != ph0) xcd_barrier(xb); run_phase<(k)>(kp, shm); }
; __device__ __forceinline__ void xcd_barrier(const XcdBarrier& b) {
;     asm volatile("s_waitcnt vmcnt(0)" ::: "memory");
;     __syncthreads();
;     if (threadIdx.x == 0) {
;         unsigned* bar = b.bar;
;         __builtin_amdgcn_s_waitcnt(0);
;         unsigned nloc = b.st[0], nx = b.st[1];
;         if (nloc == 0u) { xcd_barrier_complete(bar, b.x, nloc, nx); b.st[0] = nloc; b.st[1] = nx; }
; __global__ void __launch_bounds__(512, 2) mega(Params P, int ph0, int ph1) {
;     ...
;     RUN_PH(0) RUN_PH(1) RUN_PH(2) RUN_PH(3) RUN_PH(4) RUN_PH(5) RUN_PH(6) RUN_PH(7) RUN_PH(8) RUN_PH(9)
;     RUN_PH(10) RUN_PH(11) RUN_PH(12) RUN_PH(13) RUN_PH(14) RUN_PH(15) RUN_PH(16) RUN_PH(17)
.LBB0_436:
	s_cmp_gt_i32 s94, 3
	s_cselect_b64 s[0:1], -1, 0
	s_cmp_lt_i32 s95, 4
	s_cselect_b64 s[2:3], -1, 0
	s_or_b64 s[0:1], s[0:1], s[2:3]
	s_and_b64 vcc, exec, s[0:1]
	s_cbranch_vccnz .LBB0_508
	s_cmp_eq_u32 s94, 3
	s_cbranch_scc1 .LBB0_491
	s_waitcnt vmcnt(0)
	s_waitcnt vmcnt(0) lgkmcnt(0)
	v_cmp_lt_u32_e32 vcc, 63, v0
	s_and_saveexec_b64 s[0:1], vcc
	s_getpc_b64 s[2:3]
	v_lshlrev_b32_e32 v1, 6, v0
	v_min_u32_e32 v1, 0x7fc0, v1
	global_load_dword v1, v1, s[2:3] offset:-4096
	s_mov_b64 exec, s[0:1]
	s_barrier
	s_and_saveexec_b64 s[4:5], s[92:93]
	s_cbranch_execz .LBB0_490
	v_mov_b32_e32 v1, 0
	s_waitcnt vmcnt(0) expcnt(0) lgkmcnt(0)
	ds_read_b32 v3, v1
	ds_read_b32 v2, v1 offset:4
	s_waitcnt lgkmcnt(1)
	v_cmp_ne_u32_e32 vcc, 0, v3
	s_cbranch_vccnz .LBB0_454
	s_add_u32 s6, s88, 0x2e9d8200
	s_addc_u32 s7, s89, 0
	s_add_u32 s8, s88, 0x2e9d8400
	s_addc_u32 s9, s89, 0
	s_add_u32 s12, s88, 0x2e9d8500
	s_addc_u32 s13, s89, 0
	s_add_u32 s14, s88, 0x2e9d8600
	s_addc_u32 s15, s89, 0
	s_add_u32 s16, s88, 0x2e9d8700
	s_addc_u32 s17, s89, 0
	s_add_u32 s18, s88, 0x2e9d8800
	s_addc_u32 s19, s89, 0
	s_add_u32 s20, s88, 0x2e9d8900
	s_addc_u32 s21, s89, 0
	s_add_u32 s22, s88, 0x2e9d8a00
	s_addc_u32 s23, s89, 0
	s_add_u32 s24, s88, 0x2e9d8b00
	s_addc_u32 s25, s89, 0
	s_add_u32 s26, s88, 0x2e9d8c00
	s_addc_u32 s27, s89, 0
	s_add_u32 s28, s88, 0x2e9d8d00
	s_addc_u32 s29, s89, 0
	s_add_u32 s34, s88, 0x2e9d8e00
	s_addc_u32 s35, s89, 0
	s_add_u32 s36, s88, 0x2e9d8f00
	s_addc_u32 s37, s89, 0
	s_add_u32 s38, s88, 0x2e9d9000
	s_addc_u32 s39, s89, 0
	s_load_dwordx2 s[0:1], s[86:87], 0xe0
	s_load_dword s2, s[86:87], 0xe8
	s_add_u32 s40, s88, 0x2e9d9100
	s_addc_u32 s41, s89, 0
	s_add_u32 s42, s88, 0x2e9d9200
	s_addc_u32 s43, s89, 0
	s_waitcnt lgkmcnt(0)
	s_mul_i32 s0, s1, s0
	s_add_u32 s44, s88, 0x2e9d9300
	s_mul_i32 s0, s0, s2
	s_addc_u32 s45, s89, 0
	s_mov_b32 s1, 1
	s_branch .LBB0_442

; #define RUN_PH(k) if (ph0 <= (k) && (k) < ph1) { if ((k) != ph0) xcd_barrier(xb); run_phase<(k)>(kp, shm); }
; __device__ __forceinline__ void xcd_barrier(const XcdBarrier& b) {
;     asm volatile("s_waitcnt vmcnt(0)" ::: "memory");
;     __syncthreads();
;     if (threadIdx.x == 0) {
;         unsigned* bar = b.bar;
;         __builtin_amdgcn_s_waitcnt(0);
;         unsigned nloc = b.st[0], nx = b.st[1];
;         if (nloc == 0u) { xcd_barrier_complete(bar, b.x, nloc, nx); b.st[0] = nloc; b.st[1] = nx; }
; __global__ void __launch_bounds__(512, 2) mega(Params P, int ph0, int ph1) {
;     ...
;     RUN_PH(0) RUN_PH(1) RUN_PH(2) RUN_PH(3) RUN_PH(4) RUN_PH(5) RUN_PH(6) RUN_PH(7) RUN_PH(8) RUN_PH(9)
;     RUN_PH(10) RUN_PH(11) RUN_PH(12) RUN_PH(13) RUN_PH(14) RUN_PH(15) RUN_PH(16) RUN_PH(17)
.LBB0_508:
	s_cmp_gt_i32 s94, 4
	s_waitcnt lgkmcnt(0)
	s_cselect_b64 s[0:1], -1, 0
	s_cmp_lt_i32 s95, 5
	s_cselect_b64 s[2:3], -1, 0
	s_or_b64 s[0:1], s[0:1], s[2:3]
	s_and_b64 vcc, exec, s[0:1]
	s_cbranch_vccnz .LBB0_585
	s_cmp_eq_u32 s94, 4
	s_cbranch_scc1 .LBB0_563
	s_waitcnt vmcnt(0)
	s_waitcnt vmcnt(0)
	v_cmp_lt_u32_e32 vcc, 63, v0
	s_and_saveexec_b64 s[0:1], vcc
	s_getpc_b64 s[2:3]
	v_lshlrev_b32_e32 v1, 6, v0
	v_min_u32_e32 v1, 0x7fc0, v1
	global_load_dword v1, v1, s[2:3] offset:-4096
	s_mov_b64 exec, s[0:1]
	s_barrier
	s_and_saveexec_b64 s[4:5], s[92:93]
	s_cbranch_execz .LBB0_562
	v_mov_b32_e32 v1, 0
	s_waitcnt vmcnt(0) expcnt(0) lgkmcnt(0)
	ds_read_b32 v3, v1
	ds_read_b32 v2, v1 offset:4
	s_waitcnt lgkmcnt(1)
	v_cmp_ne_u32_e32 vcc, 0, v3
	s_cbranch_vccnz .LBB0_526
	s_add_u32 s6, s88, 0x2e9d8200
	s_addc_u32 s7, s89, 0
	s_add_u32 s8, s88, 0x2e9d8400
	s_addc_u32 s9, s89, 0
	s_add_u32 s12, s88, 0x2e9d8500
	s_addc_u32 s13, s89, 0
	s_add_u32 s14, s88, 0x2e9d8600
	s_addc_u32 s15, s89, 0
	s_add_u32 s16, s88, 0x2e9d8700
	s_addc_u32 s17, s89, 0
	s_add_u32 s18, s88, 0x2e9d8800
	s_addc_u32 s19, s89, 0
	s_add_u32 s20, s88, 0x2e9d8900
	s_addc_u32 s21, s89, 0
	s_add_u32 s22, s88, 0x2e9d8a00
	s_addc_u32 s23, s89, 0
	s_add_u32 s24, s88, 0x2e9d8b00
	s_addc_u32 s25, s89, 0
	s_add_u32 s26, s88, 0x2e9d8c00
	s_addc_u32 s27, s89, 0
	s_add_u32 s28, s88, 0x2e9d8d00
	s_addc_u32 s29, s89, 0
	s_add_u32 s34, s88, 0x2e9d8e00
	s_addc_u32 s35, s89, 0
	s_add_u32 s36, s88, 0x2e9d8f00
	s_addc_u32 s37, s89, 0
	s_add_u32 s38, s88, 0x2e9d9000
	s_addc_u32 s39, s89, 0
	s_load_dwordx2 s[0:1], s[86:87], 0xe0
	s_load_dword s2, s[86:87], 0xe8
	s_add_u32 s40, s88, 0x2e9d9100
	s_addc_u32 s41, s89, 0
	s_add_u32 s42, s88, 0x2e9d9200
	s_addc_u32 s43, s89, 0
	s_waitcnt lgkmcnt(0)
	s_mul_i32 s0, s1, s0
	s_add_u32 s44, s88, 0x2e9d9300
	s_mul_i32 s0, s0, s2
	s_addc_u32 s45, s89, 0
	s_mov_b32 s1, 1
	s_branch .LBB0_514

; #define RUN_PH(k) if (ph0 <= (k) && (k) < ph1) { if ((k) != ph0) xcd_barrier(xb); run_phase<(k)>(kp, shm); }
; __device__ __forceinline__ void xcd_barrier(const XcdBarrier& b) {
;     asm volatile("s_waitcnt vmcnt(0)" ::: "memory");
;     __syncthreads();
;     if (threadIdx.x == 0) {
;         unsigned* bar = b.bar;
;         __builtin_amdgcn_s_waitcnt(0);
;         unsigned nloc = b.st[0], nx = b.st[1];
;         if (nloc == 0u) { xcd_barrier_complete(bar, b.x, nloc, nx); b.st[0] = nloc; b.st[1] = nx; }
; __global__ void __launch_bounds__(512, 2) mega(Params P, int ph0, int ph1) {
;     ...
;     RUN_PH(0) RUN_PH(1) RUN_PH(2) RUN_PH(3) RUN_PH(4) RUN_PH(5) RUN_PH(6) RUN_PH(7) RUN_PH(8) RUN_PH(9)
;     RUN_PH(10) RUN_PH(11) RUN_PH(12) RUN_PH(13) RUN_PH(14) RUN_PH(15) RUN_PH(16) RUN_PH(17)
.LBB0_585:
	s_cmp_gt_i32 s94, 5
	s_cselect_b64 s[0:1], -1, 0
	s_cmp_lt_i32 s95, 6
	s_cselect_b64 s[2:3], -1, 0
	s_or_b64 s[0:1], s[0:1], s[2:3]
	s_and_b64 vcc, exec, s[0:1]
	s_cbranch_vccnz .LBB0_657
	s_cmp_eq_u32 s94, 5
	s_cbranch_scc1 .LBB0_640
	s_waitcnt vmcnt(0)
	s_waitcnt vmcnt(0)
	v_cmp_lt_u32_e32 vcc, 63, v0
	s_and_saveexec_b64 s[0:1], vcc
	s_getpc_b64 s[2:3]
	v_lshlrev_b32_e32 v1, 6, v0
	v_min_u32_e32 v1, 0x7fc0, v1
	global_load_dword v1, v1, s[2:3] offset:-4096
	s_mov_b64 exec, s[0:1]
	s_barrier
	s_and_saveexec_b64 s[4:5], s[92:93]
	s_cbranch_execz .LBB0_639
	v_mov_b32_e32 v1, 0
	s_waitcnt vmcnt(0) expcnt(0) lgkmcnt(0)
	ds_read_b32 v3, v1
	ds_read_b32 v2, v1 offset:4
	s_waitcnt lgkmcnt(1)
	v_cmp_ne_u32_e32 vcc, 0, v3
	s_cbranch_vccnz .LBB0_603
	s_add_u32 s6, s88, 0x2e9d8200
	s_addc_u32 s7, s89, 0
	s_add_u32 s8, s88, 0x2e9d8400
	s_addc_u32 s9, s89, 0
	s_add_u32 s12, s88, 0x2e9d8500
	s_addc_u32 s13, s89, 0
	s_add_u32 s14, s88, 0x2e9d8600
	s_addc_u32 s15, s89, 0
	s_add_u32 s16, s88, 0x2e9d8700
	s_addc_u32 s17, s89, 0
	s_add_u32 s18, s88, 0x2e9d8800
	s_addc_u32 s19, s89, 0
	s_add_u32 s20, s88, 0x2e9d8900
	s_addc_u32 s21, s89, 0
	s_add_u32 s22, s88, 0x2e9d8a00
	s_addc_u32 s23, s89, 0
	s_add_u32 s24, s88, 0x2e9d8b00
	s_addc_u32 s25, s89, 0
	s_add_u32 s26, s88, 0x2e9d8c00
	s_addc_u32 s27, s89, 0
	s_add_u32 s28, s88, 0x2e9d8d00
	s_addc_u32 s29, s89, 0
	s_add_u32 s34, s88, 0x2e9d8e00
	s_addc_u32 s35, s89, 0
	s_add_u32 s36, s88, 0x2e9d8f00
	s_addc_u32 s37, s89, 0
	s_add_u32 s38, s88, 0x2e9d9000
	s_addc_u32 s39, s89, 0
	s_load_dwordx2 s[0:1], s[86:87], 0xe0
	s_load_dword s2, s[86:87], 0xe8
	s_add_u32 s40, s88, 0x2e9d9100
	s_addc_u32 s41, s89, 0
	s_add_u32 s42, s88, 0x2e9d9200
	s_addc_u32 s43, s89, 0
	s_waitcnt lgkmcnt(0)
	s_mul_i32 s0, s1, s0
	s_add_u32 s44, s88, 0x2e9d9300
	s_mul_i32 s0, s0, s2
	s_addc_u32 s45, s89, 0
	s_mov_b32 s1, 1
	s_branch .LBB0_591

; #define RUN_PH(k) if (ph0 <= (k) && (k) < ph1) { if ((k) != ph0) xcd_barrier(xb); run_phase<(k)>(kp, shm); }
; __device__ __forceinline__ void xcd_barrier(const XcdBarrier& b) {
;     asm volatile("s_waitcnt vmcnt(0)" ::: "memory");
;     __syncthreads();
;     if (threadIdx.x == 0) {
;         unsigned* bar = b.bar;
;         __builtin_amdgcn_s_waitcnt(0);
;         unsigned nloc = b.st[0], nx = b.st[1];
;         if (nloc == 0u) { xcd_barrier_complete(bar, b.x, nloc, nx); b.st[0] = nloc; b.st[1] = nx; }
; __global__ void __launch_bounds__(512, 2) mega(Params P, int ph0, int ph1) {
;     ...
;     RUN_PH(0) RUN_PH(1) RUN_PH(2) RUN_PH(3) RUN_PH(4) RUN_PH(5) RUN_PH(6) RUN_PH(7) RUN_PH(8) RUN_PH(9)
;     RUN_PH(10) RUN_PH(11) RUN_PH(12) RUN_PH(13) RUN_PH(14) RUN_PH(15) RUN_PH(16) RUN_PH(17)
.LBB0_657:
	s_cmp_gt_i32 s94, 6
	s_waitcnt lgkmcnt(0)
	s_cselect_b64 s[0:1], -1, 0
	s_cmp_lt_i32 s95, 7
	s_cselect_b64 s[2:3], -1, 0
	s_or_b64 s[0:1], s[0:1], s[2:3]
	s_and_b64 vcc, exec, s[0:1]
	s_cbranch_vccnz .LBB0_766
	s_cmp_eq_u32 s94, 6
	s_cbranch_scc1 .LBB0_712
	s_waitcnt vmcnt(0)
	s_waitcnt vmcnt(0)
	v_cmp_lt_u32_e32 vcc, 63, v0
	s_and_saveexec_b64 s[0:1], vcc
	s_getpc_b64 s[2:3]
	v_lshlrev_b32_e32 v1, 6, v0
	v_min_u32_e32 v1, 0x7fc0, v1
	global_load_dword v1, v1, s[2:3] offset:-4096
	s_mov_b64 exec, s[0:1]
	s_barrier
	s_and_saveexec_b64 s[4:5], s[92:93]
	s_cbranch_execz .LBB0_711
	v_mov_b32_e32 v1, 0
	s_waitcnt vmcnt(0) expcnt(0) lgkmcnt(0)
	ds_read_b32 v3, v1
	ds_read_b32 v2, v1 offset:4
	s_waitcnt lgkmcnt(1)
	v_cmp_ne_u32_e32 vcc, 0, v3
	s_cbranch_vccnz .LBB0_675
	s_add_u32 s6, s88, 0x2e9d8200
	s_addc_u32 s7, s89, 0
	s_add_u32 s8, s88, 0x2e9d8400
	s_addc_u32 s9, s89, 0
	s_add_u32 s12, s88, 0x2e9d8500
	s_addc_u32 s13, s89, 0
	s_add_u32 s14, s88, 0x2e9d8600
	s_addc_u32 s15, s89, 0
	s_add_u32 s16, s88, 0x2e9d8700
	s_addc_u32 s17, s89, 0
	s_add_u32 s18, s88, 0x2e9d8800
	s_addc_u32 s19, s89, 0
	s_add_u32 s20, s88, 0x2e9d8900
	s_addc_u32 s21, s89, 0
	s_add_u32 s22, s88, 0x2e9d8a00
	s_addc_u32 s23, s89, 0
	s_add_u32 s24, s88, 0x2e9d8b00
	s_addc_u32 s25, s89, 0
	s_add_u32 s26, s88, 0x2e9d8c00
	s_addc_u32 s27, s89, 0
	s_add_u32 s28, s88, 0x2e9d8d00
	s_addc_u32 s29, s89, 0
	s_add_u32 s34, s88, 0x2e9d8e00
	s_addc_u32 s35, s89, 0
	s_add_u32 s36, s88, 0x2e9d8f00
	s_addc_u32 s37, s89, 0
	s_add_u32 s38, s88, 0x2e9d9000
	s_addc_u32 s39, s89, 0
	s_load_dwordx2 s[0:1], s[86:87], 0xe0
	s_load_dword s2, s[86:87], 0xe8
	s_add_u32 s40, s88, 0x2e9d9100
	s_addc_u32 s41, s89, 0
	s_add_u32 s42, s88, 0x2e9d9200
	s_addc_u32 s43, s89, 0
	s_waitcnt lgkmcnt(0)
	s_mul_i32 s0, s1, s0
	s_add_u32 s44, s88, 0x2e9d9300
	s_mul_i32 s0, s0, s2
	s_addc_u32 s45, s89, 0
	s_mov_b32 s1, 1
	s_branch .LBB0_663

; #define RUN_PH(k) if (ph0 <= (k) && (k) < ph1) { if ((k) != ph0) xcd_barrier(xb); run_phase<(k)>(kp, shm); }
; __device__ __forceinline__ void xcd_barrier(const XcdBarrier& b) {
;     asm volatile("s_waitcnt vmcnt(0)" ::: "memory");
;     __syncthreads();
;     if (threadIdx.x == 0) {
;         unsigned* bar = b.bar;
;         __builtin_amdgcn_s_waitcnt(0);
;         unsigned nloc = b.st[0], nx = b.st[1];
;         if (nloc == 0u) { xcd_barrier_complete(bar, b.x, nloc, nx); b.st[0] = nloc; b.st[1] = nx; }
; __global__ void __launch_bounds__(512, 2) mega(Params P, int ph0, int ph1) {
;     ...
;     RUN_PH(0) RUN_PH(1) RUN_PH(2) RUN_PH(3) RUN_PH(4) RUN_PH(5) RUN_PH(6) RUN_PH(7) RUN_PH(8) RUN_PH(9)
;     RUN_PH(10) RUN_PH(11) RUN_PH(12) RUN_PH(13) RUN_PH(14) RUN_PH(15) RUN_PH(16) RUN_PH(17)
.LBB0_766:
	s_cmp_gt_i32 s94, 7
	s_cselect_b64 s[0:1], -1, 0
	s_cmp_lt_i32 s95, 8
	s_cselect_b64 s[2:3], -1, 0
	s_or_b64 s[0:1], s[0:1], s[2:3]
	s_and_b64 vcc, exec, s[0:1]
	s_cbranch_vccnz .LBB0_879
	s_cmp_eq_u32 s94, 7
	s_cbranch_scc1 .LBB0_821
	s_waitcnt vmcnt(0)
	s_waitcnt vmcnt(0) lgkmcnt(0)
	v_cmp_lt_u32_e32 vcc, 63, v0
	s_and_saveexec_b64 s[0:1], vcc
	s_getpc_b64 s[2:3]
	v_lshlrev_b32_e32 v1, 6, v0
	v_min_u32_e32 v1, 0x7fc0, v1
	global_load_dword v1, v1, s[2:3] offset:-4096
	s_mov_b64 exec, s[0:1]
	s_barrier
	s_and_saveexec_b64 s[4:5], s[92:93]
	s_cbranch_execz .LBB0_820
	v_mov_b32_e32 v1, 0
	s_waitcnt vmcnt(0) expcnt(0) lgkmcnt(0)
	ds_read_b32 v3, v1
	ds_read_b32 v2, v1 offset:4
	s_waitcnt lgkmcnt(1)
	v_cmp_ne_u32_e32 vcc, 0, v3
	s_cbranch_vccnz .LBB0_784
	s_add_u32 s6, s88, 0x2e9d8200
	s_addc_u32 s7, s89, 0
	s_add_u32 s8, s88, 0x2e9d8400
	s_addc_u32 s9, s89, 0
	s_add_u32 s12, s88, 0x2e9d8500
	s_addc_u32 s13, s89, 0
	s_add_u32 s14, s88, 0x2e9d8600
	s_addc_u32 s15, s89, 0
	s_add_u32 s16, s88, 0x2e9d8700
	s_addc_u32 s17, s89, 0
	s_add_u32 s18, s88, 0x2e9d8800
	s_addc_u32 s19, s89, 0
	s_add_u32 s20, s88, 0x2e9d8900
	s_addc_u32 s21, s89, 0
	s_add_u32 s22, s88, 0x2e9d8a00
	s_addc_u32 s23, s89, 0
	s_add_u32 s24, s88, 0x2e9d8b00
	s_addc_u32 s25, s89, 0
	s_add_u32 s26, s88, 0x2e9d8c00
	s_addc_u32 s27, s89, 0
	s_add_u32 s28, s88, 0x2e9d8d00
	s_addc_u32 s29, s89, 0
	s_add_u32 s34, s88, 0x2e9d8e00
	s_addc_u32 s35, s89, 0
	s_add_u32 s36, s88, 0x2e9d8f00
	s_addc_u32 s37, s89, 0
	s_add_u32 s38, s88, 0x2e9d9000
	s_addc_u32 s39, s89, 0
	s_load_dwordx2 s[0:1], s[86:87], 0xe0
	s_load_dword s2, s[86:87], 0xe8
	s_add_u32 s40, s88, 0x2e9d9100
	s_addc_u32 s41, s89, 0
	s_add_u32 s42, s88, 0x2e9d9200
	s_addc_u32 s43, s89, 0
	s_waitcnt lgkmcnt(0)
	s_mul_i32 s0, s1, s0
	s_add_u32 s44, s88, 0x2e9d9300
	s_mul_i32 s0, s0, s2
	s_addc_u32 s45, s89, 0
	s_mov_b32 s1, 1
	s_branch .LBB0_772

; #define RUN_PH(k) if (ph0 <= (k) && (k) < ph1) { if ((k) != ph0) xcd_barrier(xb); run_phase<(k)>(kp, shm); }
; __device__ __forceinline__ void xcd_barrier(const XcdBarrier& b) {
;     asm volatile("s_waitcnt vmcnt(0)" ::: "memory");
;     __syncthreads();
;     if (threadIdx.x == 0) {
;         unsigned* bar = b.bar;
;         __builtin_amdgcn_s_waitcnt(0);
;         unsigned nloc = b.st[0], nx = b.st[1];
;         if (nloc == 0u) { xcd_barrier_complete(bar, b.x, nloc, nx); b.st[0] = nloc; b.st[1] = nx; }
; __global__ void __launch_bounds__(512, 2) mega(Params P, int ph0, int ph1) {
;     ...
;     RUN_PH(0) RUN_PH(1) RUN_PH(2) RUN_PH(3) RUN_PH(4) RUN_PH(5) RUN_PH(6) RUN_PH(7) RUN_PH(8) RUN_PH(9)
;     RUN_PH(10) RUN_PH(11) RUN_PH(12) RUN_PH(13) RUN_PH(14) RUN_PH(15) RUN_PH(16) RUN_PH(17)
.LBB0_879:
	s_cmp_gt_i32 s94, 8
	s_cselect_b64 s[0:1], -1, 0
	s_cmp_lt_i32 s95, 9
	s_cselect_b64 s[2:3], -1, 0
	s_or_b64 s[0:1], s[0:1], s[2:3]
	s_and_b64 vcc, exec, s[0:1]
	s_cbranch_vccnz .LBB0_962
	s_cmp_eq_u32 s94, 8
	s_cbranch_scc1 .LBB0_934
	s_waitcnt vmcnt(0)
	s_waitcnt vmcnt(0) lgkmcnt(0)
	v_cmp_lt_u32_e32 vcc, 63, v0
	s_and_saveexec_b64 s[0:1], vcc
	s_getpc_b64 s[2:3]
	v_lshlrev_b32_e32 v1, 6, v0
	v_min_u32_e32 v1, 0x7fc0, v1
	global_load_dword v1, v1, s[2:3] offset:-4096
	s_mov_b64 exec, s[0:1]
	s_barrier
	s_and_saveexec_b64 s[4:5], s[92:93]
	s_cbranch_execz .LBB0_933
	v_mov_b32_e32 v1, 0
	s_waitcnt vmcnt(0) expcnt(0) lgkmcnt(0)
	ds_read_b32 v3, v1
	ds_read_b32 v2, v1 offset:4
	s_waitcnt lgkmcnt(1)
	v_cmp_ne_u32_e32 vcc, 0, v3
	s_cbranch_vccnz .LBB0_897
	s_add_u32 s6, s88, 0x2e9d8200
	s_addc_u32 s7, s89, 0
	s_add_u32 s8, s88, 0x2e9d8400
	s_addc_u32 s9, s89, 0
	s_add_u32 s12, s88, 0x2e9d8500
	s_addc_u32 s13, s89, 0
	s_add_u32 s14, s88, 0x2e9d8600
	s_addc_u32 s15, s89, 0
	s_add_u32 s16, s88, 0x2e9d8700
	s_addc_u32 s17, s89, 0
	s_add_u32 s18, s88, 0x2e9d8800
	s_addc_u32 s19, s89, 0
	s_add_u32 s20, s88, 0x2e9d8900
	s_addc_u32 s21, s89, 0
	s_add_u32 s22, s88, 0x2e9d8a00
	s_addc_u32 s23, s89, 0
	s_add_u32 s24, s88, 0x2e9d8b00
	s_addc_u32 s25, s89, 0
	s_add_u32 s26, s88, 0x2e9d8c00
	s_addc_u32 s27, s89, 0
	s_add_u32 s28, s88, 0x2e9d8d00
	s_addc_u32 s29, s89, 0
	s_add_u32 s34, s88, 0x2e9d8e00
	s_addc_u32 s35, s89, 0
	s_add_u32 s36, s88, 0x2e9d8f00
	s_addc_u32 s37, s89, 0
	s_add_u32 s38, s88, 0x2e9d9000
	s_addc_u32 s39, s89, 0
	s_load_dwordx2 s[0:1], s[86:87], 0xe0
	s_load_dword s2, s[86:87], 0xe8
	s_add_u32 s40, s88, 0x2e9d9100
	s_addc_u32 s41, s89, 0
	s_add_u32 s42, s88, 0x2e9d9200
	s_addc_u32 s43, s89, 0
	s_waitcnt lgkmcnt(0)
	s_mul_i32 s0, s1, s0
	s_add_u32 s44, s88, 0x2e9d9300
	s_mul_i32 s0, s0, s2
	s_addc_u32 s45, s89, 0
	s_mov_b32 s1, 1
	s_branch .LBB0_885

; #define RUN_PH(k) if (ph0 <= (k) && (k) < ph1) { if ((k) != ph0) xcd_barrier(xb); run_phase<(k)>(kp, shm); }
; __device__ __forceinline__ void xcd_barrier(const XcdBarrier& b) {
;     asm volatile("s_waitcnt vmcnt(0)" ::: "memory");
;     __syncthreads();
;     if (threadIdx.x == 0) {
;         unsigned* bar = b.bar;
;         __builtin_amdgcn_s_waitcnt(0);
;         unsigned nloc = b.st[0], nx = b.st[1];
;         if (nloc == 0u) { xcd_barrier_complete(bar, b.x, nloc, nx); b.st[0] = nloc; b.st[1] = nx; }
; __global__ void __launch_bounds__(512, 2) mega(Params P, int ph0, int ph1) {
;     ...
;     RUN_PH(0) RUN_PH(1) RUN_PH(2) RUN_PH(3) RUN_PH(4) RUN_PH(5) RUN_PH(6) RUN_PH(7) RUN_PH(8) RUN_PH(9)
;     RUN_PH(10) RUN_PH(11) RUN_PH(12) RUN_PH(13) RUN_PH(14) RUN_PH(15) RUN_PH(16) RUN_PH(17)
.LBB0_962:
	s_cmp_gt_i32 s94, 9
	s_waitcnt lgkmcnt(0)
	s_cselect_b64 s[0:1], -1, 0
	s_cmp_lt_i32 s95, 10
	s_cselect_b64 s[2:3], -1, 0
	s_or_b64 s[0:1], s[0:1], s[2:3]
	s_and_b64 vcc, exec, s[0:1]
	s_cbranch_vccnz .LBB0_1023
	s_cmp_eq_u32 s94, 9
	s_cbranch_scc1 .LBB0_1017
	s_waitcnt vmcnt(0)
	s_waitcnt vmcnt(0)
	v_cmp_lt_u32_e32 vcc, 63, v0
	s_and_saveexec_b64 s[0:1], vcc
	s_getpc_b64 s[2:3]
	v_lshlrev_b32_e32 v1, 6, v0
	v_min_u32_e32 v1, 0x7fc0, v1
	global_load_dword v1, v1, s[2:3] offset:-4096
	s_mov_b64 exec, s[0:1]
	s_barrier
	s_and_saveexec_b64 s[4:5], s[92:93]
	s_cbranch_execz .LBB0_1016
	v_mov_b32_e32 v1, 0
	s_waitcnt vmcnt(0) expcnt(0) lgkmcnt(0)
	ds_read_b32 v3, v1
	ds_read_b32 v2, v1 offset:4
	s_waitcnt lgkmcnt(1)
	v_cmp_ne_u32_e32 vcc, 0, v3
	s_cbranch_vccnz .LBB0_980
	s_add_u32 s6, s88, 0x2e9d8200
	s_addc_u32 s7, s89, 0
	s_add_u32 s8, s88, 0x2e9d8400
	s_addc_u32 s9, s89, 0
	s_add_u32 s12, s88, 0x2e9d8500
	s_addc_u32 s13, s89, 0
	s_add_u32 s14, s88, 0x2e9d8600
	s_addc_u32 s15, s89, 0
	s_add_u32 s16, s88, 0x2e9d8700
	s_addc_u32 s17, s89, 0
	s_add_u32 s18, s88, 0x2e9d8800
	s_addc_u32 s19, s89, 0
	s_add_u32 s20, s88, 0x2e9d8900
	s_addc_u32 s21, s89, 0
	s_add_u32 s22, s88, 0x2e9d8a00
	s_addc_u32 s23, s89, 0
	s_add_u32 s24, s88, 0x2e9d8b00
	s_addc_u32 s25, s89, 0
	s_add_u32 s26, s88, 0x2e9d8c00
	s_addc_u32 s27, s89, 0
	s_add_u32 s28, s88, 0x2e9d8d00
	s_addc_u32 s29, s89, 0
	s_add_u32 s34, s88, 0x2e9d8e00
	s_addc_u32 s35, s89, 0
	s_add_u32 s36, s88, 0x2e9d8f00
	s_addc_u32 s37, s89, 0
	s_add_u32 s38, s88, 0x2e9d9000
	s_addc_u32 s39, s89, 0
	s_load_dwordx2 s[0:1], s[86:87], 0xe0
	s_load_dword s2, s[86:87], 0xe8
	s_add_u32 s40, s88, 0x2e9d9100
	s_addc_u32 s41, s89, 0
	s_add_u32 s42, s88, 0x2e9d9200
	s_addc_u32 s43, s89, 0
	s_waitcnt lgkmcnt(0)
	s_mul_i32 s0, s1, s0
	s_add_u32 s44, s88, 0x2e9d9300
	s_mul_i32 s0, s0, s2
	s_addc_u32 s45, s89, 0
	s_mov_b32 s1, 1
	s_branch .LBB0_968

; #define RUN_PH(k) if (ph0 <= (k) && (k) < ph1) { if ((k) != ph0) xcd_barrier(xb); run_phase<(k)>(kp, shm); }
; __device__ __forceinline__ void xcd_barrier(const XcdBarrier& b) {
;     asm volatile("s_waitcnt vmcnt(0)" ::: "memory");
;     __syncthreads();
;     if (threadIdx.x == 0) {
;         unsigned* bar = b.bar;
;         __builtin_amdgcn_s_waitcnt(0);
;         unsigned nloc = b.st[0], nx = b.st[1];
;         if (nloc == 0u) { xcd_barrier_complete(bar, b.x, nloc, nx); b.st[0] = nloc; b.st[1] = nx; }
; __global__ void __launch_bounds__(512, 2) mega(Params P, int ph0, int ph1) {
;     ...
;     RUN_PH(0) RUN_PH(1) RUN_PH(2) RUN_PH(3) RUN_PH(4) RUN_PH(5) RUN_PH(6) RUN_PH(7) RUN_PH(8) RUN_PH(9)
;     RUN_PH(10) RUN_PH(11) RUN_PH(12) RUN_PH(13) RUN_PH(14) RUN_PH(15) RUN_PH(16) RUN_PH(17)
.LBB0_1023:
	s_cmp_gt_i32 s94, 10
	s_cselect_b64 s[0:1], -1, 0
	s_cmp_lt_i32 s95, 11
	s_cselect_b64 s[2:3], -1, 0
	s_or_b64 s[0:1], s[0:1], s[2:3]
	s_and_b64 vcc, exec, s[0:1]
	s_cbranch_vccnz .LBB0_1114
	s_cmp_eq_u32 s94, 10
	s_cbranch_scc1 .LBB0_1078
	s_waitcnt vmcnt(0)
	s_waitcnt vmcnt(0)
	v_cmp_lt_u32_e32 vcc, 63, v0
	s_and_saveexec_b64 s[0:1], vcc
	s_getpc_b64 s[2:3]
	v_lshlrev_b32_e32 v1, 6, v0
	v_min_u32_e32 v1, 0x7fc0, v1
	global_load_dword v1, v1, s[2:3] offset:-4096
	s_mov_b64 exec, s[0:1]
	s_barrier
	s_and_saveexec_b64 s[4:5], s[92:93]
	s_cbranch_execz .LBB0_1077
	v_mov_b32_e32 v1, 0
	s_waitcnt vmcnt(0) expcnt(0) lgkmcnt(0)
	ds_read_b32 v3, v1
	ds_read_b32 v2, v1 offset:4
	s_waitcnt lgkmcnt(1)
	v_cmp_ne_u32_e32 vcc, 0, v3
	s_cbranch_vccnz .LBB0_1041
	s_add_u32 s6, s88, 0x2e9d8200
	s_addc_u32 s7, s89, 0
	s_add_u32 s8, s88, 0x2e9d8400
	s_addc_u32 s9, s89, 0
	s_add_u32 s12, s88, 0x2e9d8500
	s_addc_u32 s13, s89, 0
	s_add_u32 s14, s88, 0x2e9d8600
	s_addc_u32 s15, s89, 0
	s_add_u32 s16, s88, 0x2e9d8700
	s_addc_u32 s17, s89, 0
	s_add_u32 s18, s88, 0x2e9d8800
	s_addc_u32 s19, s89, 0
	s_add_u32 s20, s88, 0x2e9d8900
	s_addc_u32 s21, s89, 0
	s_add_u32 s22, s88, 0x2e9d8a00
	s_addc_u32 s23, s89, 0
	s_add_u32 s24, s88, 0x2e9d8b00
	s_addc_u32 s25, s89, 0
	s_add_u32 s26, s88, 0x2e9d8c00
	s_addc_u32 s27, s89, 0
	s_add_u32 s28, s88, 0x2e9d8d00
	s_addc_u32 s29, s89, 0
	s_add_u32 s34, s88, 0x2e9d8e00
	s_addc_u32 s35, s89, 0
	s_add_u32 s36, s88, 0x2e9d8f00
	s_addc_u32 s37, s89, 0
	s_add_u32 s38, s88, 0x2e9d9000
	s_addc_u32 s39, s89, 0
	s_load_dwordx2 s[0:1], s[86:87], 0xe0
	s_load_dword s2, s[86:87], 0xe8
	s_add_u32 s40, s88, 0x2e9d9100
	s_addc_u32 s41, s89, 0
	s_add_u32 s42, s88, 0x2e9d9200
	s_addc_u32 s43, s89, 0
	s_waitcnt lgkmcnt(0)
	s_mul_i32 s0, s1, s0
	s_add_u32 s44, s88, 0x2e9d9300
	s_mul_i32 s0, s0, s2
	s_addc_u32 s45, s89, 0
	s_mov_b32 s1, 1
	s_branch .LBB0_1029

; #define RUN_PH(k) if (ph0 <= (k) && (k) < ph1) { if ((k) != ph0) xcd_barrier(xb); run_phase<(k)>(kp, shm); }
; __device__ __forceinline__ void xcd_barrier(const XcdBarrier& b) {
;     asm volatile("s_waitcnt vmcnt(0)" ::: "memory");
;     __syncthreads();
;     if (threadIdx.x == 0) {
;         unsigned* bar = b.bar;
;         __builtin_amdgcn_s_waitcnt(0);
;         unsigned nloc = b.st[0], nx = b.st[1];
;         if (nloc == 0u) { xcd_barrier_complete(bar, b.x, nloc, nx); b.st[0] = nloc; b.st[1] = nx; }
; __global__ void __launch_bounds__(512, 2) mega(Params P, int ph0, int ph1) {
;     ...
;     RUN_PH(0) RUN_PH(1) RUN_PH(2) RUN_PH(3) RUN_PH(4) RUN_PH(5) RUN_PH(6) RUN_PH(7) RUN_PH(8) RUN_PH(9)
;     RUN_PH(10) RUN_PH(11) RUN_PH(12) RUN_PH(13) RUN_PH(14) RUN_PH(15) RUN_PH(16) RUN_PH(17)
.LBB0_1114:
	s_cmp_gt_i32 s94, 11
	s_waitcnt lgkmcnt(0)
	s_cselect_b64 s[0:1], -1, 0
	s_cmp_lt_i32 s95, 12
	s_cselect_b64 s[2:3], -1, 0
	s_or_b64 s[0:1], s[0:1], s[2:3]
	s_and_b64 vcc, exec, s[0:1]
	s_cbranch_vccnz .LBB0_1186
	s_cmp_eq_u32 s94, 11
	s_cbranch_scc1 .LBB0_1169
	s_waitcnt vmcnt(0)
	s_waitcnt vmcnt(0)
	v_cmp_lt_u32_e32 vcc, 63, v0
	s_and_saveexec_b64 s[0:1], vcc
	s_getpc_b64 s[2:3]
	v_lshlrev_b32_e32 v1, 6, v0
	v_min_u32_e32 v1, 0x7fc0, v1
	global_load_dword v1, v1, s[2:3] offset:-4096
	s_mov_b64 exec, s[0:1]
	s_barrier
	s_and_saveexec_b64 s[4:5], s[92:93]
	s_cbranch_execz .LBB0_1168
	v_mov_b32_e32 v1, 0
	s_waitcnt vmcnt(0) expcnt(0) lgkmcnt(0)
	ds_read_b32 v3, v1
	ds_read_b32 v2, v1 offset:4
	s_waitcnt lgkmcnt(1)
	v_cmp_ne_u32_e32 vcc, 0, v3
	s_cbranch_vccnz .LBB0_1132
	s_add_u32 s6, s88, 0x2e9d8200
	s_addc_u32 s7, s89, 0
	s_add_u32 s8, s88, 0x2e9d8400
	s_addc_u32 s9, s89, 0
	s_add_u32 s12, s88, 0x2e9d8500
	s_addc_u32 s13, s89, 0
	s_add_u32 s14, s88, 0x2e9d8600
	s_addc_u32 s15, s89, 0
	s_add_u32 s16, s88, 0x2e9d8700
	s_addc_u32 s17, s89, 0
	s_add_u32 s18, s88, 0x2e9d8800
	s_addc_u32 s19, s89, 0
	s_add_u32 s20, s88, 0x2e9d8900
	s_addc_u32 s21, s89, 0
	s_add_u32 s22, s88, 0x2e9d8a00
	s_addc_u32 s23, s89, 0
	s_add_u32 s24, s88, 0x2e9d8b00
	s_addc_u32 s25, s89, 0
	s_add_u32 s26, s88, 0x2e9d8c00
	s_addc_u32 s27, s89, 0
	s_add_u32 s28, s88, 0x2e9d8d00
	s_addc_u32 s29, s89, 0
	s_add_u32 s34, s88, 0x2e9d8e00
	s_addc_u32 s35, s89, 0
	s_add_u32 s36, s88, 0x2e9d8f00
	s_addc_u32 s37, s89, 0
	s_add_u32 s38, s88, 0x2e9d9000
	s_addc_u32 s39, s89, 0
	s_load_dwordx2 s[0:1], s[86:87], 0xe0
	s_load_dword s2, s[86:87], 0xe8
	s_add_u32 s40, s88, 0x2e9d9100
	s_addc_u32 s41, s89, 0
	s_add_u32 s42, s88, 0x2e9d9200
	s_addc_u32 s43, s89, 0
	s_waitcnt lgkmcnt(0)
	s_mul_i32 s0, s1, s0
	s_add_u32 s44, s88, 0x2e9d9300
	s_mul_i32 s0, s0, s2
	s_addc_u32 s45, s89, 0
	s_mov_b32 s1, 1
	s_branch .LBB0_1120

; #define RUN_PH(k) if (ph0 <= (k) && (k) < ph1) { if ((k) != ph0) xcd_barrier(xb); run_phase<(k)>(kp, shm); }
; __device__ __forceinline__ void xcd_barrier(const XcdBarrier& b) {
;     asm volatile("s_waitcnt vmcnt(0)" ::: "memory");
;     __syncthreads();
;     if (threadIdx.x == 0) {
;         unsigned* bar = b.bar;
;         __builtin_amdgcn_s_waitcnt(0);
;         unsigned nloc = b.st[0], nx = b.st[1];
;         if (nloc == 0u) { xcd_barrier_complete(bar, b.x, nloc, nx); b.st[0] = nloc; b.st[1] = nx; }
; __global__ void __launch_bounds__(512, 2) mega(Params P, int ph0, int ph1) {
;     ...
;     RUN_PH(0) RUN_PH(1) RUN_PH(2) RUN_PH(3) RUN_PH(4) RUN_PH(5) RUN_PH(6) RUN_PH(7) RUN_PH(8) RUN_PH(9)
;     RUN_PH(10) RUN_PH(11) RUN_PH(12) RUN_PH(13) RUN_PH(14) RUN_PH(15) RUN_PH(16) RUN_PH(17)
.LBB0_1186:
	s_cmp_gt_i32 s94, 12
	s_waitcnt lgkmcnt(0)
	s_cselect_b64 s[0:1], -1, 0
	s_cmp_lt_i32 s95, 13
	s_cselect_b64 s[2:3], -1, 0
	s_or_b64 s[0:1], s[0:1], s[2:3]
	s_and_b64 vcc, exec, s[0:1]
	s_cbranch_vccnz .LBB0_1255
	s_cmp_eq_u32 s94, 12
	s_cbranch_scc1 .LBB0_1241
	s_waitcnt vmcnt(0)
	s_waitcnt vmcnt(0)
	v_cmp_lt_u32_e32 vcc, 63, v0
	s_and_saveexec_b64 s[0:1], vcc
	s_getpc_b64 s[2:3]
	v_lshlrev_b32_e32 v1, 6, v0
	v_min_u32_e32 v1, 0x7fc0, v1
	global_load_dword v1, v1, s[2:3] offset:-4096
	s_mov_b64 exec, s[0:1]
	s_barrier
	s_and_saveexec_b64 s[4:5], s[92:93]
	s_cbranch_execz .LBB0_1240
	v_mov_b32_e32 v1, 0
	s_waitcnt vmcnt(0) expcnt(0) lgkmcnt(0)
	ds_read_b32 v3, v1
	ds_read_b32 v2, v1 offset:4
	s_waitcnt lgkmcnt(1)
	v_cmp_ne_u32_e32 vcc, 0, v3
	s_cbranch_vccnz .LBB0_1204
	s_add_u32 s6, s88, 0x2e9d8200
	s_addc_u32 s7, s89, 0
	s_add_u32 s8, s88, 0x2e9d8400
	s_addc_u32 s9, s89, 0
	s_add_u32 s12, s88, 0x2e9d8500
	s_addc_u32 s13, s89, 0
	s_add_u32 s14, s88, 0x2e9d8600
	s_addc_u32 s15, s89, 0
	s_add_u32 s16, s88, 0x2e9d8700
	s_addc_u32 s17, s89, 0
	s_add_u32 s18, s88, 0x2e9d8800
	s_addc_u32 s19, s89, 0
	s_add_u32 s20, s88, 0x2e9d8900
	s_addc_u32 s21, s89, 0
	s_add_u32 s22, s88, 0x2e9d8a00
	s_addc_u32 s23, s89, 0
	s_add_u32 s24, s88, 0x2e9d8b00
	s_addc_u32 s25, s89, 0
	s_add_u32 s26, s88, 0x2e9d8c00
	s_addc_u32 s27, s89, 0
	s_add_u32 s28, s88, 0x2e9d8d00
	s_addc_u32 s29, s89, 0
	s_add_u32 s34, s88, 0x2e9d8e00
	s_addc_u32 s35, s89, 0
	s_add_u32 s36, s88, 0x2e9d8f00
	s_addc_u32 s37, s89, 0
	s_add_u32 s38, s88, 0x2e9d9000
	s_addc_u32 s39, s89, 0
	s_load_dwordx2 s[0:1], s[86:87], 0xe0
	s_load_dword s2, s[86:87], 0xe8
	s_add_u32 s40, s88, 0x2e9d9100
	s_addc_u32 s41, s89, 0
	s_add_u32 s42, s88, 0x2e9d9200
	s_addc_u32 s43, s89, 0
	s_waitcnt lgkmcnt(0)
	s_mul_i32 s0, s1, s0
	s_add_u32 s44, s88, 0x2e9d9300
	s_mul_i32 s0, s0, s2
	s_addc_u32 s45, s89, 0
	s_mov_b32 s1, 1
	s_branch .LBB0_1192

; #define RUN_PH(k) if (ph0 <= (k) && (k) < ph1) { if ((k) != ph0) xcd_barrier(xb); run_phase<(k)>(kp, shm); }
; __device__ __forceinline__ void xcd_barrier(const XcdBarrier& b) {
;     asm volatile("s_waitcnt vmcnt(0)" ::: "memory");
;     __syncthreads();
;     if (threadIdx.x == 0) {
;         unsigned* bar = b.bar;
;         __builtin_amdgcn_s_waitcnt(0);
;         unsigned nloc = b.st[0], nx = b.st[1];
;         if (nloc == 0u) { xcd_barrier_complete(bar, b.x, nloc, nx); b.st[0] = nloc; b.st[1] = nx; }
; __global__ void __launch_bounds__(512, 2) mega(Params P, int ph0, int ph1) {
;     ...
;     RUN_PH(0) RUN_PH(1) RUN_PH(2) RUN_PH(3) RUN_PH(4) RUN_PH(5) RUN_PH(6) RUN_PH(7) RUN_PH(8) RUN_PH(9)
;     RUN_PH(10) RUN_PH(11) RUN_PH(12) RUN_PH(13) RUN_PH(14) RUN_PH(15) RUN_PH(16) RUN_PH(17)
.LBB0_1255:
	s_cmp_gt_i32 s94, 13
	s_waitcnt lgkmcnt(0)
	s_cselect_b64 s[0:1], -1, 0
	s_cmp_lt_i32 s95, 14
	s_cselect_b64 s[2:3], -1, 0
	s_or_b64 s[0:1], s[0:1], s[2:3]
	s_and_b64 vcc, exec, s[0:1]
	s_cbranch_vccnz .LBB0_1327
	s_cmp_eq_u32 s94, 13
	s_cbranch_scc1 .LBB0_1310
	s_waitcnt vmcnt(0)
	s_waitcnt vmcnt(0)
	v_cmp_lt_u32_e32 vcc, 63, v0
	s_and_saveexec_b64 s[0:1], vcc
	s_getpc_b64 s[2:3]
	v_lshlrev_b32_e32 v1, 6, v0
	v_min_u32_e32 v1, 0x7fc0, v1
	global_load_dword v1, v1, s[2:3] offset:-4096
	s_mov_b64 exec, s[0:1]
	s_barrier
	s_and_saveexec_b64 s[4:5], s[92:93]
	s_cbranch_execz .LBB0_1309
	v_mov_b32_e32 v1, 0
	s_waitcnt vmcnt(0) expcnt(0) lgkmcnt(0)
	ds_read_b32 v3, v1
	ds_read_b32 v2, v1 offset:4
	s_waitcnt lgkmcnt(1)
	v_cmp_ne_u32_e32 vcc, 0, v3
	s_cbranch_vccnz .LBB0_1273
	s_add_u32 s6, s88, 0x2e9d8200
	s_addc_u32 s7, s89, 0
	s_add_u32 s8, s88, 0x2e9d8400
	s_addc_u32 s9, s89, 0
	s_add_u32 s12, s88, 0x2e9d8500
	s_addc_u32 s13, s89, 0
	s_add_u32 s14, s88, 0x2e9d8600
	s_addc_u32 s15, s89, 0
	s_add_u32 s16, s88, 0x2e9d8700
	s_addc_u32 s17, s89, 0
	s_add_u32 s18, s88, 0x2e9d8800
	s_addc_u32 s19, s89, 0
	s_add_u32 s20, s88, 0x2e9d8900
	s_addc_u32 s21, s89, 0
	s_add_u32 s22, s88, 0x2e9d8a00
	s_addc_u32 s23, s89, 0
	s_add_u32 s24, s88, 0x2e9d8b00
	s_addc_u32 s25, s89, 0
	s_add_u32 s26, s88, 0x2e9d8c00
	s_addc_u32 s27, s89, 0
	s_add_u32 s28, s88, 0x2e9d8d00
	s_addc_u32 s29, s89, 0
	s_add_u32 s34, s88, 0x2e9d8e00
	s_addc_u32 s35, s89, 0
	s_add_u32 s36, s88, 0x2e9d8f00
	s_addc_u32 s37, s89, 0
	s_add_u32 s38, s88, 0x2e9d9000
	s_addc_u32 s39, s89, 0
	s_load_dwordx2 s[0:1], s[86:87], 0xe0
	s_load_dword s2, s[86:87], 0xe8
	s_add_u32 s40, s88, 0x2e9d9100
	s_addc_u32 s41, s89, 0
	s_add_u32 s42, s88, 0x2e9d9200
	s_addc_u32 s43, s89, 0
	s_waitcnt lgkmcnt(0)
	s_mul_i32 s0, s1, s0
	s_add_u32 s44, s88, 0x2e9d9300
	s_mul_i32 s0, s0, s2
	s_addc_u32 s45, s89, 0
	s_mov_b32 s1, 1
	s_branch .LBB0_1261

; #define RUN_PH(k) if (ph0 <= (k) && (k) < ph1) { if ((k) != ph0) xcd_barrier(xb); run_phase<(k)>(kp, shm); }
; __device__ __forceinline__ void xcd_barrier(const XcdBarrier& b) {
;     asm volatile("s_waitcnt vmcnt(0)" ::: "memory");
;     __syncthreads();
;     if (threadIdx.x == 0) {
;         unsigned* bar = b.bar;
;         __builtin_amdgcn_s_waitcnt(0);
;         unsigned nloc = b.st[0], nx = b.st[1];
;         if (nloc == 0u) { xcd_barrier_complete(bar, b.x, nloc, nx); b.st[0] = nloc; b.st[1] = nx; }
; __global__ void __launch_bounds__(512, 2) mega(Params P, int ph0, int ph1) {
;     ...
;     RUN_PH(0) RUN_PH(1) RUN_PH(2) RUN_PH(3) RUN_PH(4) RUN_PH(5) RUN_PH(6) RUN_PH(7) RUN_PH(8) RUN_PH(9)
;     RUN_PH(10) RUN_PH(11) RUN_PH(12) RUN_PH(13) RUN_PH(14) RUN_PH(15) RUN_PH(16) RUN_PH(17)
.LBB0_1327:
	s_cmp_gt_i32 s94, 14
	s_waitcnt lgkmcnt(0)
	s_cselect_b64 s[0:1], -1, 0
	s_cmp_lt_i32 s95, 15
	s_cselect_b64 s[2:3], -1, 0
	s_or_b64 s[0:1], s[0:1], s[2:3]
	s_and_b64 vcc, exec, s[0:1]
	s_cbranch_vccnz .LBB0_1420
	s_cmp_eq_u32 s94, 14
	s_cbranch_scc1 .LBB0_1382
	s_waitcnt vmcnt(0)
	s_waitcnt vmcnt(0)
	v_cmp_lt_u32_e32 vcc, 63, v0
	s_and_saveexec_b64 s[0:1], vcc
	s_getpc_b64 s[2:3]
	v_lshlrev_b32_e32 v1, 6, v0
	v_min_u32_e32 v1, 0x7fc0, v1
	global_load_dword v1, v1, s[2:3] offset:-4096
	s_mov_b64 exec, s[0:1]
	s_barrier
	s_and_saveexec_b64 s[4:5], s[92:93]
	s_cbranch_execz .LBB0_1381
	v_mov_b32_e32 v1, 0
	s_waitcnt vmcnt(0) expcnt(0) lgkmcnt(0)
	ds_read_b32 v3, v1
	ds_read_b32 v2, v1 offset:4
	s_waitcnt lgkmcnt(1)
	v_cmp_ne_u32_e32 vcc, 0, v3
	s_cbranch_vccnz .LBB0_1345
	s_add_u32 s6, s88, 0x2e9d8200
	s_addc_u32 s7, s89, 0
	s_add_u32 s8, s88, 0x2e9d8400
	s_addc_u32 s9, s89, 0
	s_add_u32 s12, s88, 0x2e9d8500
	s_addc_u32 s13, s89, 0
	s_add_u32 s14, s88, 0x2e9d8600
	s_addc_u32 s15, s89, 0
	s_add_u32 s16, s88, 0x2e9d8700
	s_addc_u32 s17, s89, 0
	s_add_u32 s18, s88, 0x2e9d8800
	s_addc_u32 s19, s89, 0
	s_add_u32 s20, s88, 0x2e9d8900
	s_addc_u32 s21, s89, 0
	s_add_u32 s22, s88, 0x2e9d8a00
	s_addc_u32 s23, s89, 0
	s_add_u32 s24, s88, 0x2e9d8b00
	s_addc_u32 s25, s89, 0
	s_add_u32 s26, s88, 0x2e9d8c00
	s_addc_u32 s27, s89, 0
	s_add_u32 s28, s88, 0x2e9d8d00
	s_addc_u32 s29, s89, 0
	s_add_u32 s34, s88, 0x2e9d8e00
	s_addc_u32 s35, s89, 0
	s_add_u32 s36, s88, 0x2e9d8f00
	s_addc_u32 s37, s89, 0
	s_add_u32 s38, s88, 0x2e9d9000
	s_addc_u32 s39, s89, 0
	s_load_dwordx2 s[0:1], s[86:87], 0xe0
	s_load_dword s2, s[86:87], 0xe8
	s_add_u32 s40, s88, 0x2e9d9100
	s_addc_u32 s41, s89, 0
	s_add_u32 s42, s88, 0x2e9d9200
	s_addc_u32 s43, s89, 0
	s_waitcnt lgkmcnt(0)
	s_mul_i32 s0, s1, s0
	s_add_u32 s44, s88, 0x2e9d9300
	s_mul_i32 s0, s0, s2
	s_addc_u32 s45, s89, 0
	s_mov_b32 s1, 1
	s_branch .LBB0_1333

; #define RUN_PH(k) if (ph0 <= (k) && (k) < ph1) { if ((k) != ph0) xcd_barrier(xb); run_phase<(k)>(kp, shm); }
; __device__ __forceinline__ void xcd_barrier(const XcdBarrier& b) {
;     asm volatile("s_waitcnt vmcnt(0)" ::: "memory");
;     __syncthreads();
;     if (threadIdx.x == 0) {
;         unsigned* bar = b.bar;
;         __builtin_amdgcn_s_waitcnt(0);
;         unsigned nloc = b.st[0], nx = b.st[1];
;         if (nloc == 0u) { xcd_barrier_complete(bar, b.x, nloc, nx); b.st[0] = nloc; b.st[1] = nx; }
; __global__ void __launch_bounds__(512, 2) mega(Params P, int ph0, int ph1) {
;     ...
;     RUN_PH(0) RUN_PH(1) RUN_PH(2) RUN_PH(3) RUN_PH(4) RUN_PH(5) RUN_PH(6) RUN_PH(7) RUN_PH(8) RUN_PH(9)
;     RUN_PH(10) RUN_PH(11) RUN_PH(12) RUN_PH(13) RUN_PH(14) RUN_PH(15) RUN_PH(16) RUN_PH(17)
.LBB0_1420:
	s_cmp_gt_i32 s94, 15
	s_cselect_b64 s[0:1], -1, 0
	s_cmp_lt_i32 s95, 16
	s_cselect_b64 s[2:3], -1, 0
	s_or_b64 s[0:1], s[0:1], s[2:3]
	s_and_b64 vcc, exec, s[0:1]
	s_cbranch_vccnz .LBB0_1523
	s_cmp_eq_u32 s94, 15
	s_cbranch_scc1 .LBB0_1475
	s_waitcnt vmcnt(0)
	s_waitcnt vmcnt(0) lgkmcnt(0)
	v_cmp_lt_u32_e32 vcc, 63, v0
	s_and_saveexec_b64 s[0:1], vcc
	s_getpc_b64 s[2:3]
	v_lshlrev_b32_e32 v1, 6, v0
	v_min_u32_e32 v1, 0x6e40, v1
	global_load_dword v1, v1, s[2:3] offset:-4096
	s_mov_b64 exec, s[0:1]
	s_barrier
	s_and_saveexec_b64 s[4:5], s[92:93]
	s_cbranch_execz .LBB0_1474
	v_mov_b32_e32 v1, 0
	s_waitcnt vmcnt(0) expcnt(0) lgkmcnt(0)
	ds_read_b32 v3, v1
	ds_read_b32 v2, v1 offset:4
	s_waitcnt lgkmcnt(1)
	v_cmp_ne_u32_e32 vcc, 0, v3
	s_cbranch_vccnz .LBB0_1438
	s_add_u32 s6, s88, 0x2e9d8200
	s_addc_u32 s7, s89, 0
	s_add_u32 s8, s88, 0x2e9d8400
	s_addc_u32 s9, s89, 0
	s_add_u32 s12, s88, 0x2e9d8500
	s_addc_u32 s13, s89, 0
	s_add_u32 s14, s88, 0x2e9d8600
	s_addc_u32 s15, s89, 0
	s_add_u32 s16, s88, 0x2e9d8700
	s_addc_u32 s17, s89, 0
	s_add_u32 s18, s88, 0x2e9d8800
	s_addc_u32 s19, s89, 0
	s_add_u32 s20, s88, 0x2e9d8900
	s_addc_u32 s21, s89, 0
	s_add_u32 s22, s88, 0x2e9d8a00
	s_addc_u32 s23, s89, 0
	s_add_u32 s24, s88, 0x2e9d8b00
	s_addc_u32 s25, s89, 0
	s_add_u32 s26, s88, 0x2e9d8c00
	s_addc_u32 s27, s89, 0
	s_add_u32 s28, s88, 0x2e9d8d00
	s_addc_u32 s29, s89, 0
	s_add_u32 s34, s88, 0x2e9d8e00
	s_addc_u32 s35, s89, 0
	s_add_u32 s36, s88, 0x2e9d8f00
	s_addc_u32 s37, s89, 0
	s_add_u32 s38, s88, 0x2e9d9000
	s_addc_u32 s39, s89, 0
	s_load_dwordx2 s[0:1], s[86:87], 0xe0
	s_load_dword s2, s[86:87], 0xe8
	s_add_u32 s40, s88, 0x2e9d9100
	s_addc_u32 s41, s89, 0
	s_add_u32 s42, s88, 0x2e9d9200
	s_addc_u32 s43, s89, 0
	s_waitcnt lgkmcnt(0)
	s_mul_i32 s0, s1, s0
	s_add_u32 s44, s88, 0x2e9d9300
	s_mul_i32 s0, s0, s2
	s_addc_u32 s45, s89, 0
	s_mov_b32 s1, 1
	s_branch .LBB0_1426

; #define RUN_PH(k) if (ph0 <= (k) && (k) < ph1) { if ((k) != ph0) xcd_barrier(xb); run_phase<(k)>(kp, shm); }
; __device__ __forceinline__ void xcd_barrier(const XcdBarrier& b) {
;     asm volatile("s_waitcnt vmcnt(0)" ::: "memory");
;     __syncthreads();
;     if (threadIdx.x == 0) {
;         unsigned* bar = b.bar;
;         __builtin_amdgcn_s_waitcnt(0);
;         unsigned nloc = b.st[0], nx = b.st[1];
;         if (nloc == 0u) { xcd_barrier_complete(bar, b.x, nloc, nx); b.st[0] = nloc; b.st[1] = nx; }
; __global__ void __launch_bounds__(512, 2) mega(Params P, int ph0, int ph1) {
;     ...
;     RUN_PH(0) RUN_PH(1) RUN_PH(2) RUN_PH(3) RUN_PH(4) RUN_PH(5) RUN_PH(6) RUN_PH(7) RUN_PH(8) RUN_PH(9)
;     RUN_PH(10) RUN_PH(11) RUN_PH(12) RUN_PH(13) RUN_PH(14) RUN_PH(15) RUN_PH(16) RUN_PH(17)
.LBB0_1523:
	s_cmp_gt_i32 s94, 16
	s_cselect_b64 s[0:1], -1, 0
	s_cmp_lt_i32 s95, 17
	s_cselect_b64 s[2:3], -1, 0
	s_or_b64 s[0:1], s[0:1], s[2:3]
	s_and_b64 vcc, exec, s[0:1]
	s_cbranch_vccnz .LBB0_1598
	s_cmp_eq_u32 s94, 16
	s_cbranch_scc1 .LBB0_1578
	s_waitcnt vmcnt(0)
	s_waitcnt vmcnt(0) lgkmcnt(0)
	v_cmp_lt_u32_e32 vcc, 63, v0
	s_and_saveexec_b64 s[0:1], vcc
	s_getpc_b64 s[2:3]
	v_lshlrev_b32_e32 v1, 6, v0
	v_min_u32_e32 v1, 0x37c0, v1
	global_load_dword v1, v1, s[2:3] offset:-4096
	s_mov_b64 exec, s[0:1]
	s_barrier
	s_and_saveexec_b64 s[4:5], s[92:93]
	s_cbranch_execz .LBB0_1577
	v_mov_b32_e32 v1, 0
	s_waitcnt vmcnt(0) expcnt(0) lgkmcnt(0)
	ds_read_b32 v3, v1
	ds_read_b32 v2, v1 offset:4
	s_waitcnt lgkmcnt(1)
	v_cmp_ne_u32_e32 vcc, 0, v3
	s_cbranch_vccnz .LBB0_1541
	s_add_u32 s6, s88, 0x2e9d8200
	s_addc_u32 s7, s89, 0
	s_add_u32 s8, s88, 0x2e9d8400
	s_addc_u32 s9, s89, 0
	s_add_u32 s12, s88, 0x2e9d8500
	s_addc_u32 s13, s89, 0
	s_add_u32 s14, s88, 0x2e9d8600
	s_addc_u32 s15, s89, 0
	s_add_u32 s16, s88, 0x2e9d8700
	s_addc_u32 s17, s89, 0
	s_add_u32 s18, s88, 0x2e9d8800
	s_addc_u32 s19, s89, 0
	s_add_u32 s20, s88, 0x2e9d8900
	s_addc_u32 s21, s89, 0
	s_add_u32 s22, s88, 0x2e9d8a00
	s_addc_u32 s23, s89, 0
	s_add_u32 s24, s88, 0x2e9d8b00
	s_addc_u32 s25, s89, 0
	s_add_u32 s26, s88, 0x2e9d8c00
	s_addc_u32 s27, s89, 0
	s_add_u32 s28, s88, 0x2e9d8d00
	s_addc_u32 s29, s89, 0
	s_add_u32 s34, s88, 0x2e9d8e00
	s_addc_u32 s35, s89, 0
	s_add_u32 s36, s88, 0x2e9d8f00
	s_addc_u32 s37, s89, 0
	s_add_u32 s38, s88, 0x2e9d9000
	s_addc_u32 s39, s89, 0
	s_load_dwordx2 s[0:1], s[86:87], 0xe0
	s_load_dword s2, s[86:87], 0xe8
	s_add_u32 s40, s88, 0x2e9d9100
	s_addc_u32 s41, s89, 0
	s_add_u32 s42, s88, 0x2e9d9200
	s_addc_u32 s43, s89, 0
	s_waitcnt lgkmcnt(0)
	s_mul_i32 s0, s1, s0
	s_add_u32 s44, s88, 0x2e9d9300
	s_mul_i32 s0, s0, s2
	s_addc_u32 s45, s89, 0
	s_mov_b32 s1, 1
	s_branch .LBB0_1529

; #define RUN_PH(k) if (ph0 <= (k) && (k) < ph1) { if ((k) != ph0) xcd_barrier(xb); run_phase<(k)>(kp, shm); }
; __device__ __forceinline__ void xcd_barrier(const XcdBarrier& b) {
;     asm volatile("s_waitcnt vmcnt(0)" ::: "memory");
;     __syncthreads();
;     if (threadIdx.x == 0) {
;         unsigned* bar = b.bar;
;         __builtin_amdgcn_s_waitcnt(0);
;         unsigned nloc = b.st[0], nx = b.st[1];
;         if (nloc == 0u) { xcd_barrier_complete(bar, b.x, nloc, nx); b.st[0] = nloc; b.st[1] = nx; }
; __global__ void __launch_bounds__(512, 2) mega(Params P, int ph0, int ph1) {
;     ...
;     RUN_PH(0) RUN_PH(1) RUN_PH(2) RUN_PH(3) RUN_PH(4) RUN_PH(5) RUN_PH(6) RUN_PH(7) RUN_PH(8) RUN_PH(9)
;     RUN_PH(10) RUN_PH(11) RUN_PH(12) RUN_PH(13) RUN_PH(14) RUN_PH(15) RUN_PH(16) RUN_PH(17)
.LBB0_1598:
	s_cmp_gt_i32 s94, 17
	s_cselect_b64 s[0:1], -1, 0
	s_cmp_lt_i32 s95, 18
	s_cselect_b64 s[2:3], -1, 0
	s_or_b64 s[0:1], s[0:1], s[2:3]
	s_and_b64 vcc, exec, s[0:1]
	s_cbranch_vccnz .LBB0_1656
	s_cmp_eq_u32 s94, 17
	s_cbranch_scc1 .LBB0_1653
	s_waitcnt vmcnt(0)
	s_waitcnt vmcnt(0) lgkmcnt(0)
	v_cmp_lt_u32_e32 vcc, 63, v0
	s_and_saveexec_b64 s[0:1], vcc
	s_getpc_b64 s[2:3]
	v_lshlrev_b32_e32 v1, 6, v0
	v_min_u32_e32 v1, 0x1b80, v1
	global_load_dword v1, v1, s[2:3] offset:-4096
	s_mov_b64 exec, s[0:1]
	s_barrier
	s_and_saveexec_b64 s[4:5], s[92:93]
	s_cbranch_execz .LBB0_1652
	v_mov_b32_e32 v1, 0
	s_waitcnt vmcnt(0) expcnt(0) lgkmcnt(0)
	ds_read_b32 v3, v1
	ds_read_b32 v2, v1 offset:4
	s_waitcnt lgkmcnt(1)
	v_cmp_ne_u32_e32 vcc, 0, v3
	s_cbranch_vccnz .LBB0_1616
	s_add_u32 s6, s88, 0x2e9d8200
	s_addc_u32 s7, s89, 0
	s_add_u32 s8, s88, 0x2e9d8400
	s_addc_u32 s9, s89, 0
	s_add_u32 s12, s88, 0x2e9d8500
	s_addc_u32 s13, s89, 0
	s_add_u32 s14, s88, 0x2e9d8600
	s_addc_u32 s15, s89, 0
	s_add_u32 s16, s88, 0x2e9d8700
	s_addc_u32 s17, s89, 0
	s_add_u32 s18, s88, 0x2e9d8800
	s_addc_u32 s19, s89, 0
	s_add_u32 s20, s88, 0x2e9d8900
	s_addc_u32 s21, s89, 0
	s_add_u32 s22, s88, 0x2e9d8a00
	s_addc_u32 s23, s89, 0
	s_add_u32 s24, s88, 0x2e9d8b00
	s_addc_u32 s25, s89, 0
	s_add_u32 s26, s88, 0x2e9d8c00
	s_addc_u32 s27, s89, 0
	s_add_u32 s28, s88, 0x2e9d8d00
	s_addc_u32 s29, s89, 0
	s_add_u32 s30, s88, 0x2e9d8e00
	s_addc_u32 s31, s89, 0
	s_add_u32 s34, s88, 0x2e9d8f00
	s_addc_u32 s35, s89, 0
	s_add_u32 s36, s88, 0x2e9d9000
	s_addc_u32 s37, s89, 0
	s_load_dwordx2 s[0:1], s[86:87], 0xe0
	s_load_dword s2, s[86:87], 0xe8
	s_add_u32 s38, s88, 0x2e9d9100
	s_addc_u32 s39, s89, 0
	s_add_u32 s40, s88, 0x2e9d9200
	s_addc_u32 s41, s89, 0
	s_waitcnt lgkmcnt(0)
	s_mul_i32 s0, s1, s0
	s_add_u32 s42, s88, 0x2e9d9300
	s_mul_i32 s0, s0, s2
	s_addc_u32 s43, s89, 0
	s_mov_b32 s1, 1
	s_branch .LBB0_1604
